# GEMM K-loops: static s_setprio 1 for waves 0-3 (older half) with the per-phase flips removed: A/B against the waves 4-7 variant
# baseline (speedup 1.0000x reference)
.LBB0_132:
	s_add_u32 s34, s28, 0x100
	v_mov_b32_e32 v0, 0
	s_addc_u32 s79, s29, 0
	s_mov_b32 s84, -2
	v_mov_b32_e32 v1, v0
	v_mov_b32_e32 v2, v0
	v_mov_b32_e32 v3, v0
	v_mov_b32_e32 v4, v0
	v_mov_b32_e32 v5, v0
	v_mov_b32_e32 v6, v0
	v_mov_b32_e32 v7, v0
	v_mov_b32_e32 v8, v0
	v_mov_b32_e32 v9, v0
	v_mov_b32_e32 v10, v0
	v_mov_b32_e32 v11, v0
	v_mov_b32_e32 v12, v0
	v_mov_b32_e32 v13, v0
	v_mov_b32_e32 v14, v0
	v_mov_b32_e32 v15, v0
	v_mov_b32_e32 v22, v0
	v_mov_b32_e32 v23, v0
	v_mov_b32_e32 v24, v0
	v_mov_b32_e32 v25, v0
	v_mov_b32_e32 v26, v0
	v_mov_b32_e32 v27, v0
	v_mov_b32_e32 v28, v0
	v_mov_b32_e32 v29, v0
	v_mov_b32_e32 v34, v0
	v_mov_b32_e32 v35, v0
	v_mov_b32_e32 v36, v0
	v_mov_b32_e32 v37, v0
	v_mov_b32_e32 v42, v0
	v_mov_b32_e32 v43, v0
	v_mov_b32_e32 v44, v0
	v_mov_b32_e32 v45, v0
	v_mov_b32_e32 v18, v0
	v_mov_b32_e32 v19, v0
	v_mov_b32_e32 v20, v0
	v_mov_b32_e32 v21, v0
	v_mov_b32_e32 v30, v0
	v_mov_b32_e32 v31, v0
	v_mov_b32_e32 v32, v0
	v_mov_b32_e32 v33, v0
	v_mov_b32_e32 v38, v0
	v_mov_b32_e32 v39, v0
	v_mov_b32_e32 v40, v0
	v_mov_b32_e32 v41, v0
	v_mov_b32_e32 v46, v0
	v_mov_b32_e32 v47, v0
	v_mov_b32_e32 v48, v0
	v_mov_b32_e32 v49, v0
	v_mov_b32_e32 v50, v0
	v_mov_b32_e32 v51, v0
	v_mov_b32_e32 v52, v0
	v_mov_b32_e32 v53, v0
	v_mov_b32_e32 v54, v0
	v_mov_b32_e32 v55, v0
	v_mov_b32_e32 v56, v0
	v_mov_b32_e32 v57, v0
	v_mov_b32_e32 v58, v0
	v_mov_b32_e32 v59, v0
	v_mov_b32_e32 v60, v0
	v_mov_b32_e32 v61, v0
	v_mov_b32_e32 v62, v0
	v_mov_b32_e32 v63, v0
	v_mov_b32_e32 v64, v0
	v_mov_b32_e32 v65, v0
	v_mov_b32_e32 v66, v0
	v_mov_b32_e32 v67, v0
	v_mov_b32_e32 v68, v0
	v_mov_b32_e32 v69, v0
	v_mov_b32_e32 v70, v0
	v_mov_b32_e32 v71, v0
	v_mov_b32_e32 v72, v0
	v_mov_b32_e32 v73, v0
	v_mov_b32_e32 v78, v0
	v_mov_b32_e32 v79, v0
	v_mov_b32_e32 v80, v0
	v_mov_b32_e32 v81, v0
	v_mov_b32_e32 v82, v0
	v_mov_b32_e32 v83, v0
	v_mov_b32_e32 v84, v0
	v_mov_b32_e32 v85, v0
	v_mov_b32_e32 v94, v0
	v_mov_b32_e32 v95, v0
	v_mov_b32_e32 v96, v0
	v_mov_b32_e32 v97, v0
	v_mov_b32_e32 v98, v0
	v_mov_b32_e32 v99, v0
	v_mov_b32_e32 v100, v0
	v_mov_b32_e32 v101, v0
	v_mov_b32_e32 v110, v0
	v_mov_b32_e32 v111, v0
	v_mov_b32_e32 v112, v0
	v_mov_b32_e32 v113, v0
	v_mov_b32_e32 v114, v0
	v_mov_b32_e32 v115, v0
	v_mov_b32_e32 v116, v0
	v_mov_b32_e32 v117, v0
	v_mov_b32_e32 v74, v0
	v_mov_b32_e32 v75, v0
	v_mov_b32_e32 v76, v0
	v_mov_b32_e32 v77, v0
	v_mov_b32_e32 v86, v0
	v_mov_b32_e32 v87, v0
	v_mov_b32_e32 v88, v0
	v_mov_b32_e32 v89, v0
	v_mov_b32_e32 v90, v0
	v_mov_b32_e32 v91, v0
	v_mov_b32_e32 v92, v0
	v_mov_b32_e32 v93, v0
	v_mov_b32_e32 v102, v0
	v_mov_b32_e32 v103, v0
	v_mov_b32_e32 v104, v0
	v_mov_b32_e32 v105, v0
	v_mov_b32_e32 v106, v0
	v_mov_b32_e32 v107, v0
	v_mov_b32_e32 v108, v0
	v_mov_b32_e32 v109, v0
	v_mov_b32_e32 v118, v0
	v_mov_b32_e32 v119, v0
	v_mov_b32_e32 v120, v0
	v_mov_b32_e32 v121, v0
	v_mov_b32_e32 v122, v0
	v_mov_b32_e32 v123, v0
	v_mov_b32_e32 v124, v0
	v_mov_b32_e32 v125, v0
	v_mov_b32_e32 v126, v0
	v_mov_b32_e32 v127, v0
	v_mov_b32_e32 v128, v0
	v_mov_b32_e32 v129, v0
	v_readfirstlane_b32 s98, v228
	s_lshr_b32 s98, s98, 8
	s_cmp_eq_u32 s98, 0
	s_cbranch_scc0 .Lprio_skip_0
	s_setprio 1

.LBB0_146:
	s_ashr_i32 s29, s28, 31
	v_cmp_lt_i64_e32 vcc, s[22:23], v[198:199]
	s_lshl_b64 s[22:23], s[28:29], 19
	s_add_u32 s40, s30, s22
	s_addc_u32 s41, s31, s23
	s_and_b64 s[22:23], vcc, exec
	s_cselect_b32 s12, s41, s19
	s_cselect_b32 s29, s40, s18
	s_ashr_i32 s9, s8, 31
	s_lshl_b64 s[22:23], s[8:9], 19
	s_add_u32 s42, s49, s22
	s_addc_u32 s43, s50, s23
	s_and_b64 s[22:23], vcc, exec
	s_cselect_b32 s9, s43, s17
	s_cselect_b32 s34, s42, s16
	s_add_u32 s61, s16, 0x100
	s_addc_u32 s79, s17, 0
	s_add_u32 s16, s18, 0x40080
	v_mov_b32_e32 v0, 0
	s_addc_u32 s17, s19, 0
	s_mov_b32 s82, -2
	v_mov_b32_e32 v1, v0
	v_mov_b32_e32 v2, v0
	v_mov_b32_e32 v3, v0
	v_mov_b32_e32 v8, v0
	v_mov_b32_e32 v9, v0
	v_mov_b32_e32 v10, v0
	v_mov_b32_e32 v11, v0
	v_mov_b32_e32 v18, v0
	v_mov_b32_e32 v19, v0
	v_mov_b32_e32 v20, v0
	v_mov_b32_e32 v21, v0
	v_mov_b32_e32 v26, v0
	v_mov_b32_e32 v27, v0
	v_mov_b32_e32 v28, v0
	v_mov_b32_e32 v29, v0
	s_waitcnt lgkmcnt(0)
	v_mov_b32_e32 v34, v0
	v_mov_b32_e32 v35, v0
	v_mov_b32_e32 v36, v0
	v_mov_b32_e32 v37, v0
	v_mov_b32_e32 v42, v0
	v_mov_b32_e32 v43, v0
	v_mov_b32_e32 v44, v0
	v_mov_b32_e32 v45, v0
	v_mov_b32_e32 v50, v0
	v_mov_b32_e32 v51, v0
	v_mov_b32_e32 v52, v0
	v_mov_b32_e32 v53, v0
	v_mov_b32_e32 v58, v0
	v_mov_b32_e32 v59, v0
	v_mov_b32_e32 v60, v0
	v_mov_b32_e32 v61, v0
	v_mov_b32_e32 v4, v0
	v_mov_b32_e32 v5, v0
	v_mov_b32_e32 v6, v0
	v_mov_b32_e32 v7, v0
	v_mov_b32_e32 v12, v0
	v_mov_b32_e32 v13, v0
	v_mov_b32_e32 v14, v0
	v_mov_b32_e32 v15, v0
	v_mov_b32_e32 v22, v0
	v_mov_b32_e32 v23, v0
	v_mov_b32_e32 v24, v0
	v_mov_b32_e32 v25, v0
	v_mov_b32_e32 v30, v0
	v_mov_b32_e32 v31, v0
	v_mov_b32_e32 v32, v0
	v_mov_b32_e32 v33, v0
	v_mov_b32_e32 v38, v0
	v_mov_b32_e32 v39, v0
	v_mov_b32_e32 v40, v0
	v_mov_b32_e32 v41, v0
	v_mov_b32_e32 v46, v0
	v_mov_b32_e32 v47, v0
	v_mov_b32_e32 v48, v0
	v_mov_b32_e32 v49, v0
	v_mov_b32_e32 v54, v0
	v_mov_b32_e32 v55, v0
	v_mov_b32_e32 v56, v0
	v_mov_b32_e32 v57, v0
	v_mov_b32_e32 v62, v0
	v_mov_b32_e32 v63, v0
	v_mov_b32_e32 v64, v0
	v_mov_b32_e32 v65, v0
	v_mov_b32_e32 v66, v0
	v_mov_b32_e32 v67, v0
	v_mov_b32_e32 v68, v0
	v_mov_b32_e32 v69, v0
	v_mov_b32_e32 v74, v0
	v_mov_b32_e32 v75, v0
	v_mov_b32_e32 v76, v0
	v_mov_b32_e32 v77, v0
	v_mov_b32_e32 v82, v0
	v_mov_b32_e32 v83, v0
	v_mov_b32_e32 v84, v0
	v_mov_b32_e32 v85, v0
	v_mov_b32_e32 v90, v0
	v_mov_b32_e32 v91, v0
	v_mov_b32_e32 v92, v0
	v_mov_b32_e32 v93, v0
	v_mov_b32_e32 v98, v0
	v_mov_b32_e32 v99, v0
	v_mov_b32_e32 v100, v0
	v_mov_b32_e32 v101, v0
	v_mov_b32_e32 v106, v0
	v_mov_b32_e32 v107, v0
	v_mov_b32_e32 v108, v0
	v_mov_b32_e32 v109, v0
	v_mov_b32_e32 v114, v0
	v_mov_b32_e32 v115, v0
	v_mov_b32_e32 v116, v0
	v_mov_b32_e32 v117, v0
	v_mov_b32_e32 v122, v0
	v_mov_b32_e32 v123, v0
	v_mov_b32_e32 v124, v0
	v_mov_b32_e32 v125, v0
	v_mov_b32_e32 v70, v0
	v_mov_b32_e32 v71, v0
	v_mov_b32_e32 v72, v0
	v_mov_b32_e32 v73, v0
	v_mov_b32_e32 v78, v0
	v_mov_b32_e32 v79, v0
	v_mov_b32_e32 v80, v0
	v_mov_b32_e32 v81, v0
	v_mov_b32_e32 v86, v0
	v_mov_b32_e32 v87, v0
	v_mov_b32_e32 v88, v0
	v_mov_b32_e32 v89, v0
	v_mov_b32_e32 v94, v0
	v_mov_b32_e32 v95, v0
	v_mov_b32_e32 v96, v0
	v_mov_b32_e32 v97, v0
	v_mov_b32_e32 v102, v0
	v_mov_b32_e32 v103, v0
	v_mov_b32_e32 v104, v0
	v_mov_b32_e32 v105, v0
	v_mov_b32_e32 v110, v0
	v_mov_b32_e32 v111, v0
	v_mov_b32_e32 v112, v0
	v_mov_b32_e32 v113, v0
	v_mov_b32_e32 v118, v0
	v_mov_b32_e32 v119, v0
	v_mov_b32_e32 v120, v0
	v_mov_b32_e32 v121, v0
	v_mov_b32_e32 v126, v0
	v_mov_b32_e32 v127, v0
	v_mov_b32_e32 v128, v0
	v_mov_b32_e32 v129, v0
	v_readfirstlane_b32 s98, v228
	s_lshr_b32 s98, s98, 8
	s_cmp_eq_u32 s98, 0
	s_cbranch_scc0 .Lprio_skip_1
	s_setprio 1

.LBB0_173:
	s_ashr_i32 s9, s8, 31
	v_cmp_lt_i64_e32 vcc, s[14:15], v[202:203]
	s_lshl_b64 s[14:15], s[8:9], 19
	s_add_u32 s14, s96, s14
	s_addc_u32 s15, s97, s15
	s_and_b64 s[16:17], vcc, exec
	s_cselect_b32 s9, s15, s23
	s_cselect_b32 s12, s14, s22
	s_ashr_i32 s5, s4, 31
	s_lshl_b64 s[16:17], s[4:5], 19
	s_add_u32 s16, s50, s16
	s_addc_u32 s17, s51, s17
	s_and_b64 s[42:43], vcc, exec
	s_cselect_b32 s5, s17, s41
	s_cselect_b32 s34, s16, s40
	s_add_u32 s61, s40, 0x100
	v_mov_b32_e32 v0, 0
	s_addc_u32 s79, s41, 0
	s_mov_b32 s82, -2
	v_mov_b32_e32 v1, v0
	v_mov_b32_e32 v2, v0
	v_mov_b32_e32 v3, v0
	v_mov_b32_e32 v4, v0
	v_mov_b32_e32 v5, v0
	v_mov_b32_e32 v6, v0
	v_mov_b32_e32 v7, v0
	v_mov_b32_e32 v8, v0
	v_mov_b32_e32 v9, v0
	v_mov_b32_e32 v10, v0
	v_mov_b32_e32 v11, v0
	v_mov_b32_e32 v12, v0
	v_mov_b32_e32 v13, v0
	v_mov_b32_e32 v14, v0
	v_mov_b32_e32 v15, v0
	v_mov_b32_e32 v22, v0
	v_mov_b32_e32 v23, v0
	v_mov_b32_e32 v24, v0
	v_mov_b32_e32 v25, v0
	v_mov_b32_e32 v26, v0
	v_mov_b32_e32 v27, v0
	v_mov_b32_e32 v28, v0
	v_mov_b32_e32 v29, v0
	v_mov_b32_e32 v34, v0
	v_mov_b32_e32 v35, v0
	v_mov_b32_e32 v36, v0
	v_mov_b32_e32 v37, v0
	v_mov_b32_e32 v42, v0
	v_mov_b32_e32 v43, v0
	v_mov_b32_e32 v44, v0
	v_mov_b32_e32 v45, v0
	v_mov_b32_e32 v18, v0
	v_mov_b32_e32 v19, v0
	v_mov_b32_e32 v20, v0
	v_mov_b32_e32 v21, v0
	v_mov_b32_e32 v30, v0
	v_mov_b32_e32 v31, v0
	v_mov_b32_e32 v32, v0
	v_mov_b32_e32 v33, v0
	v_mov_b32_e32 v38, v0
	v_mov_b32_e32 v39, v0
	v_mov_b32_e32 v40, v0
	v_mov_b32_e32 v41, v0
	v_mov_b32_e32 v46, v0
	v_mov_b32_e32 v47, v0
	v_mov_b32_e32 v48, v0
	v_mov_b32_e32 v49, v0
	v_mov_b32_e32 v50, v0
	v_mov_b32_e32 v51, v0
	v_mov_b32_e32 v52, v0
	v_mov_b32_e32 v53, v0
	v_mov_b32_e32 v54, v0
	v_mov_b32_e32 v55, v0
	v_mov_b32_e32 v56, v0
	v_mov_b32_e32 v57, v0
	v_mov_b32_e32 v58, v0
	v_mov_b32_e32 v59, v0
	v_mov_b32_e32 v60, v0
	v_mov_b32_e32 v61, v0
	v_mov_b32_e32 v62, v0
	v_mov_b32_e32 v63, v0
	v_mov_b32_e32 v64, v0
	v_mov_b32_e32 v65, v0
	v_mov_b32_e32 v66, v0
	v_mov_b32_e32 v67, v0
	v_mov_b32_e32 v68, v0
	v_mov_b32_e32 v69, v0
	v_mov_b32_e32 v70, v0
	v_mov_b32_e32 v71, v0
	v_mov_b32_e32 v72, v0
	v_mov_b32_e32 v73, v0
	v_mov_b32_e32 v78, v0
	v_mov_b32_e32 v79, v0
	v_mov_b32_e32 v80, v0
	v_mov_b32_e32 v81, v0
	v_mov_b32_e32 v82, v0
	v_mov_b32_e32 v83, v0
	v_mov_b32_e32 v84, v0
	v_mov_b32_e32 v85, v0
	v_mov_b32_e32 v94, v0
	v_mov_b32_e32 v95, v0
	v_mov_b32_e32 v96, v0
	v_mov_b32_e32 v97, v0
	v_mov_b32_e32 v98, v0
	v_mov_b32_e32 v99, v0
	v_mov_b32_e32 v100, v0
	v_mov_b32_e32 v101, v0
	v_mov_b32_e32 v110, v0
	v_mov_b32_e32 v111, v0
	v_mov_b32_e32 v112, v0
	v_mov_b32_e32 v113, v0
	v_mov_b32_e32 v114, v0
	v_mov_b32_e32 v115, v0
	v_mov_b32_e32 v116, v0
	v_mov_b32_e32 v117, v0
	v_mov_b32_e32 v74, v0
	v_mov_b32_e32 v75, v0
	v_mov_b32_e32 v76, v0
	v_mov_b32_e32 v77, v0
	v_mov_b32_e32 v86, v0
	v_mov_b32_e32 v87, v0
	v_mov_b32_e32 v88, v0
	v_mov_b32_e32 v89, v0
	v_mov_b32_e32 v90, v0
	v_mov_b32_e32 v91, v0
	v_mov_b32_e32 v92, v0
	v_mov_b32_e32 v93, v0
	v_mov_b32_e32 v102, v0
	v_mov_b32_e32 v103, v0
	v_mov_b32_e32 v104, v0
	v_mov_b32_e32 v105, v0
	v_mov_b32_e32 v106, v0
	v_mov_b32_e32 v107, v0
	v_mov_b32_e32 v108, v0
	v_mov_b32_e32 v109, v0
	v_mov_b32_e32 v118, v0
	v_mov_b32_e32 v119, v0
	v_mov_b32_e32 v120, v0
	v_mov_b32_e32 v121, v0
	v_mov_b32_e32 v122, v0
	v_mov_b32_e32 v123, v0
	v_mov_b32_e32 v124, v0
	v_mov_b32_e32 v125, v0
	v_mov_b32_e32 v126, v0
	v_mov_b32_e32 v127, v0
	v_mov_b32_e32 v128, v0
	v_mov_b32_e32 v129, v0
	v_readfirstlane_b32 s98, v228
	s_lshr_b32 s98, s98, 8
	s_cmp_eq_u32 s98, 0
	s_cbranch_scc0 .Lprio_skip_2
	s_setprio 1

.LBB0_210:
	s_ashr_i32 s91, s90, 31
	v_cmp_lt_i64_e64 s[38:39], s[4:5], v[202:203]
	s_lshl_b64 s[4:5], s[90:91], 24
	s_add_u32 s2, s50, s4
	s_addc_u32 s9, s51, s5
	s_ashr_i32 s93, s92, 31
	s_lshl_b64 s[4:5], s[92:93], 18
	s_add_u32 s56, s2, s4
	s_addc_u32 s57, s9, s5
	s_and_b64 s[4:5], s[38:39], exec
	s_cselect_b32 s2, s57, s19
	s_cselect_b32 s9, s56, s18
	s_lshl_b64 s[4:5], s[90:91], 20
	s_add_u32 s12, s37, s4
	s_addc_u32 s15, s48, s5
	s_ashr_i32 s55, s54, 31
	s_lshl_b64 s[4:5], s[54:55], 18
	s_add_u32 s4, s12, s4
	s_addc_u32 s5, s15, s5
	s_and_b64 s[22:23], s[38:39], exec
	s_cselect_b32 s12, s5, s17
	s_cselect_b32 s15, s4, s16
	s_add_u32 s34, s16, 0x100
	s_addc_u32 s40, s17, 0
	s_add_u32 s16, s18, 0x20080
	s_addc_u32 s17, s19, 0
	s_mov_b32 s41, -2
	v_readfirstlane_b32 s98, v228
	s_lshr_b32 s98, s98, 8
	s_cmp_eq_u32 s98, 0
	s_cbranch_scc0 .Lprio_skip_3
	s_setprio 1

.LBB0_978:
	s_ashr_i32 s9, s8, 31
	v_cmp_lt_i64_e32 vcc, s[14:15], v[206:207]
	s_lshl_b64 s[14:15], s[8:9], 19
	s_add_u32 s14, s30, s14
	s_addc_u32 s15, s31, s15
	s_and_b64 s[16:17], vcc, exec
	s_cselect_b32 s9, s15, s23
	s_cselect_b32 s56, s14, s22
	s_ashr_i32 s5, s4, 31
	s_lshl_b64 s[16:17], s[4:5], 19
	s_add_u32 s16, s44, s16
	s_addc_u32 s17, s45, s17
	s_and_b64 s[28:29], vcc, exec
	s_cselect_b32 s5, s17, s21
	s_cselect_b32 s57, s16, s20
	s_add_u32 s58, s20, 0x100
	s_addc_u32 s59, s21, 0
	s_add_u32 s20, s22, 0x40080
	v_mov_b32_e32 v26, 0
	s_addc_u32 s21, s23, 0
	s_mov_b32 s60, -2
	v_mov_b32_e32 v27, v26
	v_mov_b32_e32 v28, v26
	v_mov_b32_e32 v29, v26
	v_mov_b32_e32 v38, v26
	v_mov_b32_e32 v39, v26
	v_mov_b32_e32 v40, v26
	v_mov_b32_e32 v41, v26
	v_mov_b32_e32 v46, v26
	v_mov_b32_e32 v47, v26
	v_mov_b32_e32 v48, v26
	v_mov_b32_e32 v49, v26
	v_mov_b32_e32 v58, v26
	v_mov_b32_e32 v59, v26
	v_mov_b32_e32 v60, v26
	v_mov_b32_e32 v61, v26
	v_mov_b32_e32 v82, v26
	v_mov_b32_e32 v83, v26
	v_mov_b32_e32 v84, v26
	v_mov_b32_e32 v85, v26
	v_mov_b32_e32 v86, v26
	v_mov_b32_e32 v87, v26
	v_mov_b32_e32 v88, v26
	v_mov_b32_e32 v89, v26
	v_mov_b32_e32 v90, v26
	v_mov_b32_e32 v91, v26
	v_mov_b32_e32 v92, v26
	v_mov_b32_e32 v93, v26
	v_mov_b32_e32 v94, v26
	v_mov_b32_e32 v95, v26
	v_mov_b32_e32 v96, v26
	v_mov_b32_e32 v97, v26
	v_mov_b32_e32 v0, v26
	v_mov_b32_e32 v1, v26
	v_mov_b32_e32 v2, v26
	v_mov_b32_e32 v3, v26
	v_mov_b32_e32 v4, v26
	v_mov_b32_e32 v5, v26
	v_mov_b32_e32 v6, v26
	v_mov_b32_e32 v7, v26
	v_mov_b32_e32 v8, v26
	v_mov_b32_e32 v9, v26
	v_mov_b32_e32 v10, v26
	v_mov_b32_e32 v11, v26
	v_mov_b32_e32 v12, v26
	v_mov_b32_e32 v13, v26
	v_mov_b32_e32 v14, v26
	v_mov_b32_e32 v15, v26
	v_mov_b32_e32 v18, v26
	v_mov_b32_e32 v19, v26
	v_mov_b32_e32 v20, v26
	v_mov_b32_e32 v21, v26
	v_mov_b32_e32 v22, v26
	v_mov_b32_e32 v23, v26
	v_mov_b32_e32 v24, v26
	v_mov_b32_e32 v25, v26
	v_mov_b32_e32 v30, v26
	v_mov_b32_e32 v31, v26
	v_mov_b32_e32 v32, v26
	v_mov_b32_e32 v33, v26
	s_waitcnt lgkmcnt(0)
	v_mov_b32_e32 v34, v26
	v_mov_b32_e32 v35, v26
	v_mov_b32_e32 v36, v26
	v_mov_b32_e32 v37, v26
	v_mov_b32_e32 v98, v26
	v_mov_b32_e32 v99, v26
	v_mov_b32_e32 v100, v26
	v_mov_b32_e32 v101, v26
	v_mov_b32_e32 v102, v26
	v_mov_b32_e32 v103, v26
	v_mov_b32_e32 v104, v26
	v_mov_b32_e32 v105, v26
	v_mov_b32_e32 v106, v26
	v_mov_b32_e32 v107, v26
	v_mov_b32_e32 v108, v26
	v_mov_b32_e32 v109, v26
	v_mov_b32_e32 v110, v26
	v_mov_b32_e32 v111, v26
	v_mov_b32_e32 v112, v26
	v_mov_b32_e32 v113, v26
	v_mov_b32_e32 v114, v26
	v_mov_b32_e32 v115, v26
	v_mov_b32_e32 v116, v26
	v_mov_b32_e32 v117, v26
	v_mov_b32_e32 v118, v26
	v_mov_b32_e32 v119, v26
	v_mov_b32_e32 v120, v26
	v_mov_b32_e32 v121, v26
	v_mov_b32_e32 v122, v26
	v_mov_b32_e32 v123, v26
	v_mov_b32_e32 v124, v26
	v_mov_b32_e32 v125, v26
	v_mov_b32_e32 v126, v26
	v_mov_b32_e32 v127, v26
	v_mov_b32_e32 v128, v26
	v_mov_b32_e32 v129, v26
	v_mov_b32_e32 v42, v26
	v_mov_b32_e32 v43, v26
	v_mov_b32_e32 v44, v26
	v_mov_b32_e32 v45, v26
	v_mov_b32_e32 v50, v26
	v_mov_b32_e32 v51, v26
	v_mov_b32_e32 v52, v26
	v_mov_b32_e32 v53, v26
	v_mov_b32_e32 v54, v26
	v_mov_b32_e32 v55, v26
	v_mov_b32_e32 v56, v26
	v_mov_b32_e32 v57, v26
	v_mov_b32_e32 v62, v26
	v_mov_b32_e32 v63, v26
	v_mov_b32_e32 v64, v26
	v_mov_b32_e32 v65, v26
	v_mov_b32_e32 v66, v26
	v_mov_b32_e32 v67, v26
	v_mov_b32_e32 v68, v26
	v_mov_b32_e32 v69, v26
	v_mov_b32_e32 v70, v26
	v_mov_b32_e32 v71, v26
	v_mov_b32_e32 v72, v26
	v_mov_b32_e32 v73, v26
	v_mov_b32_e32 v74, v26
	v_mov_b32_e32 v75, v26
	v_mov_b32_e32 v76, v26
	v_mov_b32_e32 v77, v26
	v_mov_b32_e32 v78, v26
	v_mov_b32_e32 v79, v26
	v_mov_b32_e32 v80, v26
	v_mov_b32_e32 v81, v26
	v_readfirstlane_b32 s98, v228
	s_lshr_b32 s98, s98, 8
	s_cmp_eq_u32 s98, 0
	s_cbranch_scc0 .Lprio_skip_4
	s_setprio 1
